# setup modulation GEMV: non-temporal hint on the once-streamed f32 weight loads (same arithmetic)
# speedup vs baseline: 1.0053x; 1.0053x over previous
.LBB0_24:
	v_add_co_u32_e64 v166, s[8:9], s19, v154
	v_add_co_u32_e32 v164, vcc, 0xfffd3000, v154
	s_nop 0
	v_addc_co_u32_e64 v167, s[8:9], -1, v155, s[8:9]
	v_add_co_u32_e64 v168, s[8:9], s20, v154
	v_addc_co_u32_e32 v165, vcc, -1, v155, vcc
	s_nop 0
	v_addc_co_u32_e64 v169, s[8:9], -1, v155, s[8:9]
	v_add_co_u32_e64 v170, s[8:9], s21, v154
	v_add_co_u32_e32 v198, vcc, 0xfffd6000, v154
	s_nop 0
	v_addc_co_u32_e64 v171, s[8:9], -1, v155, s[8:9]
	v_add_co_u32_e64 v172, s[8:9], s22, v154
	v_addc_co_u32_e32 v199, vcc, -1, v155, vcc
	s_nop 0
	v_addc_co_u32_e64 v173, s[8:9], -1, v155, s[8:9]
	v_add_co_u32_e64 v174, s[8:9], s23, v154
	v_add_co_u32_e32 v200, vcc, 0xfffd9000, v154
	s_nop 0
	v_addc_co_u32_e64 v175, s[8:9], -1, v155, s[8:9]
	v_add_co_u32_e64 v176, s[8:9], s24, v154
	ds_read_b128 v[16:19], v195
	ds_read_b128 v[12:15], v195 offset:16
	ds_read_b128 v[8:11], v195 offset:32
	ds_read_b128 v[4:7], v195 offset:48
	v_addc_co_u32_e64 v177, s[8:9], -1, v155, s[8:9]
	v_add_co_u32_e64 v178, s[8:9], s25, v154
	ds_read_b128 v[0:3], v195 offset:4096
	ds_read_b128 v[20:23], v195 offset:4112
	ds_read_b128 v[56:59], v195 offset:8192
	ds_read_b128 v[60:63], v195 offset:8208
	ds_read_b128 v[28:31], v195 offset:12288
	ds_read_b128 v[24:27], v195 offset:12304
	ds_read_b128 v[64:67], v195 offset:16384
	ds_read_b128 v[68:71], v195 offset:16400
	ds_read_b128 v[36:39], v195 offset:20480
	ds_read_b128 v[32:35], v195 offset:20496
	ds_read_b128 v[72:75], v195 offset:24576
	ds_read_b128 v[76:79], v195 offset:24592
	ds_read_b128 v[44:47], v195 offset:28672
	ds_read_b128 v[40:43], v195 offset:28688
	ds_read_b128 v[48:51], v195 offset:32768
	ds_read_b128 v[52:55], v195 offset:32784
	v_addc_co_u32_e64 v179, s[8:9], -1, v155, s[8:9]
	v_add_co_u32_e64 v180, s[8:9], s26, v154
	global_load_dword v146, v[154:155], off nt
	s_nop 0
	v_addc_co_u32_e64 v181, s[8:9], -1, v155, s[8:9]
	v_add_co_u32_e64 v182, s[8:9], s27, v154
	ds_read_b128 v[80:83], v195 offset:4128
	ds_read_b128 v[84:87], v195 offset:4144
	ds_read_b128 v[96:99], v195 offset:8224
	ds_read_b128 v[108:111], v195 offset:8240
	ds_read_b128 v[92:95], v195 offset:12320
	ds_read_b128 v[88:91], v195 offset:12336
	ds_read_b128 v[112:115], v195 offset:16416
	ds_read_b128 v[128:131], v195 offset:16432
	ds_read_b128 v[104:107], v195 offset:20512
	ds_read_b128 v[100:103], v195 offset:20528
	ds_read_b128 v[132:135], v195 offset:24608
	ds_read_b128 v[136:139], v195 offset:24624
	ds_read_b128 v[120:123], v195 offset:28704
	ds_read_b128 v[116:119], v195 offset:28720
	ds_read_b128 v[124:127], v195 offset:32800
	ds_read_b128 v[140:143], v195 offset:32816
	v_addc_co_u32_e64 v183, s[8:9], -1, v155, s[8:9]
	v_add_co_u32_e64 v184, s[8:9], s28, v154
	v_addc_co_u32_e32 v201, vcc, -1, v155, vcc
	s_nop 0
	v_addc_co_u32_e64 v185, s[8:9], -1, v155, s[8:9]
	v_add_co_u32_e64 v186, s[8:9], s29, v154
	v_add_co_u32_e32 v202, vcc, 0xfffdc000, v154
	s_nop 0
	v_addc_co_u32_e64 v187, s[8:9], -1, v155, s[8:9]
	global_load_dword v174, v[174:175], off nt
	s_nop 0
	global_load_dword v176, v[176:177], off nt
	s_nop 0
	global_load_dword v178, v[178:179], off nt
	s_nop 0
	global_load_dword v180, v[180:181], off nt
	s_nop 0
	global_load_dword v182, v[182:183], off nt
	s_nop 0
	global_load_dword v184, v[184:185], off nt
	s_nop 0
	global_load_dword v186, v[186:187], off nt
	v_addc_co_u32_e32 v203, vcc, -1, v155, vcc
	global_load_dword v164, v[164:165], off nt
	s_nop 0
	global_load_dword v198, v[198:199], off nt
	s_nop 0
	global_load_dword v200, v[200:201], off nt
	s_waitcnt lgkmcnt(14)
	v_mov_b32_e32 v204, v16
	v_mov_b32_e32 v16, v18
	v_mov_b32_e32 v18, v56
	v_mov_b32_e32 v56, v58
	v_mov_b32_e32 v58, v64
	v_mov_b32_e32 v64, v66
	v_mov_b32_e32 v66, v72
	v_mov_b32_e32 v72, v74
	global_load_dword v74, v[202:203], off nt
	s_nop 0
	global_load_dword v166, v[166:167], off nt
	s_nop 0
	global_load_dword v168, v[168:169], off nt
	s_nop 0
	global_load_dword v170, v[170:171], off nt
	s_nop 0
	global_load_dword v172, v[172:173], off nt
	v_mov_b32_e32 v203, v20
	v_mov_b32_e32 v20, v13
	v_mov_b32_e32 v13, v22
	v_mov_b32_e32 v22, v15
	v_mov_b32_e32 v15, v24
	v_mov_b32_e32 v24, v61
	v_mov_b32_e32 v61, v26
	v_mov_b32_e32 v26, v63
	v_mov_b32_e32 v63, v32
	v_mov_b32_e32 v32, v69
	v_mov_b32_e32 v69, v34
	v_mov_b32_e32 v34, v71
	v_mov_b32_e32 v71, v40
	v_mov_b32_e32 v40, v77
	v_mov_b32_e32 v77, v42
	v_mov_b32_e32 v42, v79
	v_mov_b32_e32 v79, v80
	v_mov_b32_e32 v80, v9
	v_mov_b32_e32 v9, v82
	v_mov_b32_e32 v82, v11
	s_waitcnt lgkmcnt(11)
	v_mov_b32_e32 v11, v92
	v_mov_b32_e32 v92, v97
	v_mov_b32_e32 v97, v94
	v_mov_b32_e32 v94, v99
	s_waitcnt lgkmcnt(7)
	v_mov_b32_e32 v99, v104
	v_mov_b32_e32 v104, v113
	v_mov_b32_e32 v113, v106
	v_mov_b32_e32 v106, v115
	s_waitcnt lgkmcnt(3)
	v_mov_b32_e32 v115, v120
	v_mov_b32_e32 v120, v133
	v_mov_b32_e32 v205, v0
	v_mov_b32_e32 v0, v17
	v_mov_b32_e32 v17, v2
	v_mov_b32_e32 v2, v19
	v_mov_b32_e32 v19, v28
	v_mov_b32_e32 v28, v57
	v_mov_b32_e32 v202, v12
	v_mov_b32_e32 v12, v14
	v_mov_b32_e32 v14, v60
	v_mov_b32_e32 v60, v62
	v_mov_b32_e32 v62, v68
	v_mov_b32_e32 v68, v70
	v_mov_b32_e32 v70, v76
	v_mov_b32_e32 v76, v78
	v_mov_b32_e32 v78, v8
	v_mov_b32_e32 v8, v10
	v_mov_b32_e32 v10, v96
	v_mov_b32_e32 v96, v98
	v_mov_b32_e32 v98, v112
	v_mov_b32_e32 v112, v114
	v_mov_b32_e32 v114, v132
	v_mov_b32_e32 v57, v30
	v_mov_b32_e32 v30, v59
	v_mov_b32_e32 v59, v36
	v_mov_b32_e32 v36, v65
	v_mov_b32_e32 v65, v38
	v_mov_b32_e32 v38, v67
	v_mov_b32_e32 v67, v44
	v_mov_b32_e32 v44, v73
	v_mov_b32_e32 v132, v134
	v_mov_b32_e32 v133, v122
	s_waitcnt vmcnt(13)
	v_pk_mul_f32 v[80:81], v[176:177], v[80:81] op_sel_hi:[0,1]
	v_pk_mul_f32 v[92:93], v[176:177], v[92:93] op_sel_hi:[0,1]
	v_pk_mul_f32 v[104:105], v[176:177], v[104:105] op_sel_hi:[0,1]
	v_pk_mul_f32 v[120:121], v[176:177], v[120:121] op_sel_hi:[0,1]
	v_pk_fma_f32 v[78:79], v[174:175], v[78:79], v[80:81] op_sel_hi:[0,1,1]
	v_pk_fma_f32 v[10:11], v[174:175], v[10:11], v[92:93] op_sel_hi:[0,1,1]
	v_pk_fma_f32 v[80:81], v[174:175], v[98:99], v[104:105] op_sel_hi:[0,1,1]
	v_pk_fma_f32 v[92:93], v[174:175], v[114:115], v[120:121] op_sel_hi:[0,1,1]
	v_mov_b32_e32 v175, v176
	s_waitcnt vmcnt(6)
	v_pk_mul_f32 v[0:1], v[198:199], v[0:1] op_sel_hi:[0,1]
	v_pk_mul_f32 v[28:29], v[198:199], v[28:29] op_sel_hi:[0,1]
	v_pk_mul_f32 v[36:37], v[198:199], v[36:37] op_sel_hi:[0,1]
	v_pk_mul_f32 v[44:45], v[198:199], v[44:45] op_sel_hi:[0,1]
	v_pk_fma_f32 v[8:9], v[178:179], v[8:9], v[78:79] op_sel_hi:[0,1,1]
	v_pk_fma_f32 v[78:79], v[178:179], v[112:113], v[80:81] op_sel_hi:[0,1,1]
	v_pk_fma_f32 v[80:81], v[178:179], v[132:133], v[92:93] op_sel_hi:[0,1,1]
	s_waitcnt lgkmcnt(1)
	v_pk_mul_f32 v[92:93], v[174:175], v[124:125]
	v_pk_fma_f32 v[0:1], v[164:165], v[204:205], v[0:1] op_sel_hi:[0,1,1]
	v_pk_fma_f32 v[18:19], v[164:165], v[18:19], v[28:29] op_sel_hi:[0,1,1]
	v_mov_b32_e32 v73, v46
	v_mov_b32_e32 v46, v75
	v_pk_fma_f32 v[28:29], v[164:165], v[58:59], v[36:37] op_sel_hi:[0,1,1]
	v_pk_fma_f32 v[36:37], v[164:165], v[66:67], v[44:45] op_sel_hi:[0,1,1]
	v_mov_b32_e32 v165, v198
	v_add_f32_e32 v75, v92, v93
	s_waitcnt vmcnt(5)
	v_pk_fma_f32 v[0:1], v[200:201], v[16:17], v[0:1] op_sel_hi:[0,1,1]
	v_pk_fma_f32 v[16:17], v[200:201], v[56:57], v[18:19] op_sel_hi:[0,1,1]
	s_waitcnt vmcnt(2)
	v_pk_mul_f32 v[20:21], v[168:169], v[20:21] op_sel_hi:[0,1]
	v_pk_mul_f32 v[24:25], v[168:169], v[24:25] op_sel_hi:[0,1]
	v_pk_mul_f32 v[32:33], v[168:169], v[32:33] op_sel_hi:[0,1]
	v_pk_mul_f32 v[40:41], v[168:169], v[40:41] op_sel_hi:[0,1]
	v_mov_b32_e32 v122, v135
	v_mov_b32_e32 v135, v84
	v_mov_b32_e32 v84, v5
	v_mov_b32_e32 v5, v86
	v_mov_b32_e32 v86, v7
	v_mov_b32_e32 v7, v88
	v_mov_b32_e32 v88, v109
	v_mov_b32_e32 v109, v90
	v_mov_b32_e32 v90, v111
	v_mov_b32_e32 v111, v100
	v_mov_b32_e32 v100, v129
	v_mov_b32_e32 v129, v102
	v_mov_b32_e32 v102, v131
	v_mov_b32_e32 v131, v116
	v_mov_b32_e32 v116, v137
	v_pk_fma_f32 v[18:19], v[200:201], v[64:65], v[28:29] op_sel_hi:[0,1,1]
	v_pk_fma_f32 v[28:29], v[200:201], v[72:73], v[36:37] op_sel_hi:[0,1,1]
	v_pk_mul_f32 v[36:37], v[164:165], v[48:49]
	v_mov_b32_e32 v201, v74
	v_pk_fma_f32 v[0:1], v[74:75], v[2:3], v[0:1] op_sel_hi:[0,1,1]
	v_pk_fma_f32 v[2:3], v[74:75], v[30:31], v[16:17] op_sel_hi:[0,1,1]
	v_pk_fma_f32 v[20:21], v[166:167], v[202:203], v[20:21] op_sel_hi:[0,1,1]
	v_pk_fma_f32 v[14:15], v[166:167], v[14:15], v[24:25] op_sel_hi:[0,1,1]
	v_pk_fma_f32 v[24:25], v[166:167], v[62:63], v[32:33] op_sel_hi:[0,1,1]
	v_pk_fma_f32 v[30:31], v[166:167], v[70:71], v[40:41] op_sel_hi:[0,1,1]
	v_mov_b32_e32 v167, v168
	v_mov_b32_e32 v134, v4
	v_mov_b32_e32 v4, v6
	v_mov_b32_e32 v6, v108
	v_mov_b32_e32 v108, v110
	v_mov_b32_e32 v110, v128
	v_mov_b32_e32 v128, v130
	v_mov_b32_e32 v130, v136
	v_pk_mul_f32 v[84:85], v[184:185], v[84:85] op_sel_hi:[0,1]
	v_pk_mul_f32 v[88:89], v[184:185], v[88:89] op_sel_hi:[0,1]
	v_pk_mul_f32 v[100:101], v[184:185], v[100:101] op_sel_hi:[0,1]
	v_pk_mul_f32 v[116:117], v[184:185], v[116:117] op_sel_hi:[0,1]
	v_pk_fma_f32 v[16:17], v[74:75], v[38:39], v[18:19] op_sel_hi:[0,1,1]
	v_pk_fma_f32 v[18:19], v[74:75], v[46:47], v[28:29] op_sel_hi:[0,1,1]
	v_pk_mul_f32 v[28:29], v[200:201], v[50:51]
	v_add_f32_e32 v36, v36, v37
	s_waitcnt vmcnt(1)
	v_pk_fma_f32 v[12:13], v[170:171], v[12:13], v[20:21] op_sel_hi:[0,1,1]
	v_pk_fma_f32 v[14:15], v[170:171], v[60:61], v[14:15] op_sel_hi:[0,1,1]
	v_pk_fma_f32 v[20:21], v[170:171], v[68:69], v[24:25] op_sel_hi:[0,1,1]
	v_pk_fma_f32 v[24:25], v[170:171], v[76:77], v[30:31] op_sel_hi:[0,1,1]
	v_pk_mul_f32 v[30:31], v[166:167], v[52:53]
	s_waitcnt vmcnt(0)
	v_mov_b32_e32 v171, v172
	v_mov_b32_e32 v136, v138
	v_mov_b32_e32 v137, v118
	v_pk_fma_f32 v[84:85], v[182:183], v[134:135], v[84:85] op_sel_hi:[0,1,1]
	v_pk_fma_f32 v[6:7], v[182:183], v[6:7], v[88:89] op_sel_hi:[0,1,1]
	v_pk_fma_f32 v[88:89], v[182:183], v[110:111], v[100:101] op_sel_hi:[0,1,1]
	v_pk_fma_f32 v[98:99], v[182:183], v[130:131], v[116:117] op_sel_hi:[0,1,1]
	v_mov_b32_e32 v183, v184
	v_pk_fma_f32 v[10:11], v[178:179], v[96:97], v[10:11] op_sel_hi:[0,1,1]
	v_mov_b32_e32 v179, v180
	v_pk_add_f32 v[0:1], v[156:157], v[0:1]
	v_pk_add_f32 v[16:17], v[160:161], v[16:17]
	v_add_f32_e32 v28, v28, v36
	v_pk_fma_f32 v[12:13], v[172:173], v[22:23], v[12:13] op_sel_hi:[0,1,1]
	v_pk_fma_f32 v[14:15], v[172:173], v[26:27], v[14:15] op_sel_hi:[0,1,1]
	v_pk_fma_f32 v[20:21], v[172:173], v[34:35], v[20:21] op_sel_hi:[0,1,1]
	v_pk_fma_f32 v[22:23], v[172:173], v[42:43], v[24:25] op_sel_hi:[0,1,1]
	v_pk_mul_f32 v[24:25], v[170:171], v[54:55]
	v_add_f32_e32 v26, v30, v31
	v_pk_fma_f32 v[4:5], v[186:187], v[4:5], v[84:85] op_sel_hi:[0,1,1]
	v_pk_fma_f32 v[6:7], v[186:187], v[108:109], v[6:7] op_sel_hi:[0,1,1]
	v_pk_fma_f32 v[84:85], v[186:187], v[128:129], v[88:89] op_sel_hi:[0,1,1]
	v_pk_fma_f32 v[88:89], v[186:187], v[136:137], v[98:99] op_sel_hi:[0,1,1]
	s_waitcnt lgkmcnt(0)
	v_pk_mul_f32 v[96:97], v[182:183], v[140:141]
	v_mov_b32_e32 v187, v146
	v_pk_mul_f32 v[66:67], v[178:179], v[126:127]
	v_add_f32_e32 v28, v29, v28
	v_pk_add_f32 v[0:1], v[0:1], v[12:13]
	v_pk_add_f32 v[12:13], v[16:17], v[20:21]
	v_add_f32_e32 v16, v24, v26
	v_pk_fma_f32 v[8:9], v[180:181], v[82:83], v[8:9] op_sel_hi:[0,1,1]
	v_pk_fma_f32 v[44:45], v[180:181], v[106:107], v[78:79] op_sel_hi:[0,1,1]
	v_pk_fma_f32 v[78:79], v[146:147], v[102:103], v[84:85] op_sel_hi:[0,1,1]
	v_pk_mul_f32 v[82:83], v[186:187], v[142:143]
	v_add_f32_e32 v84, v96, v97
	v_add_f32_e32 v48, v66, v75
	v_pk_add_f32 v[2:3], v[158:159], v[2:3]
	v_pk_add_f32 v[18:19], v[162:163], v[18:19]
	v_add_f32_e32 v27, v197, v28
	v_add_f32_e32 v16, v25, v16
	v_add_u32_e32 v196, 16, v196
	v_mov_b32_e32 v118, v139
	v_pk_fma_f32 v[10:11], v[180:181], v[94:95], v[10:11] op_sel_hi:[0,1,1]
	v_pk_fma_f32 v[58:59], v[180:181], v[122:123], v[80:81] op_sel_hi:[0,1,1]
	v_pk_fma_f32 v[4:5], v[146:147], v[86:87], v[4:5] op_sel_hi:[0,1,1]
	v_add_f32_e32 v49, v82, v84
	v_add_f32_e32 v32, v67, v48
	v_pk_add_f32 v[2:3], v[2:3], v[14:15]
	v_pk_add_f32 v[14:15], v[18:19], v[22:23]
	v_pk_add_f32 v[0:1], v[0:1], v[8:9]
	v_pk_add_f32 v[8:9], v[12:13], v[44:45]
	v_add_f32_e32 v12, v27, v16
	v_cmp_ge_i32_e64 s[8:9], v196, v190
	v_pk_fma_f32 v[6:7], v[146:147], v[90:91], v[6:7] op_sel_hi:[0,1,1]
	v_pk_fma_f32 v[80:81], v[146:147], v[118:119], v[88:89] op_sel_hi:[0,1,1]
	v_add_f32_e32 v33, v83, v49
	v_pk_add_f32 v[2:3], v[2:3], v[10:11]
	v_pk_add_f32 v[10:11], v[14:15], v[58:59]
	v_pk_add_f32 v[156:157], v[0:1], v[4:5]
	v_add_f32_e32 v0, v12, v32
	v_add_u32_e32 v195, 64, v195
	s_or_b64 s[14:15], s[8:9], s[14:15]
	v_lshl_add_u64 v[154:155], v[154:155], 0, s[10:11]
	v_pk_add_f32 v[158:159], v[2:3], v[6:7]
	v_pk_add_f32 v[160:161], v[8:9], v[78:79]
	v_pk_add_f32 v[162:163], v[10:11], v[80:81]
	v_add_f32_e32 v197, v0, v33
	s_andn2_b64 exec, exec, s[14:15]
	s_cbranch_execnz .LBB0_24
	s_or_b64 exec, exec, s[14:15]
	v_add_u32_e32 v0, 0x9000, v194
	ds_write2_b32 v0, v156, v157 offset1:32
	ds_write2_b32 v0, v158, v159 offset0:64 offset1:96
	ds_write2_b32 v0, v160, v161 offset0:128 offset1:160
	ds_write2_b32 v0, v162, v163 offset0:192 offset1:224
	ds_write_b32 v194, v197 offset:37888
	s_waitcnt lgkmcnt(0)
	s_barrier
	s_and_saveexec_b64 s[8:9], s[4:5]
	s_cbranch_execz .LBB0_19
	s_load_dwordx16 s[56:71], s[0:1], 0x0
	s_mul_i32 s14, s31, 0xc00
	s_add_i32 s14, s14, s12
	v_or_b32_e32 v0, s14, v188
	v_ashrrev_i32_e32 v1, 31, v0
	s_mul_i32 s31, s31, 9
	s_waitcnt lgkmcnt(0)
	v_lshl_add_u64 v[0:1], v[0:1], 2, s[68:69]
	v_lshl_add_u64 v[2:3], s[12:13], 2, v[148:149]
	s_mov_b64 s[12:13], 0
	v_mov_b32_e32 v4, v144
